# attention: the four first-level bucket-table reads of the far-key bias lookups join the batched bias reads after QK^T
# baseline (speedup 1.0000x reference)
; __device__ __forceinline__ f32x4 mfma32(bf16x8 a, bf16x8 b, f32x4 c) { return __builtin_amdgcn_mfma_f32_16x16x32_bf16(a, b, c, 0, 0, 0); }
; __device__ __forceinline__ void attn_unit(const Ptrs& P, int l, int b, int gk, int n, unsigned char* lds, int tid, bool dost) {
;     ...
;         for (int kt = 0; kt < 9; ++kt) { const unsigned char* kp = lds + AT_KS + (16 * (qs + kt) + lc) * 144 + 16 * g;
;             const bf16x8 a0 = *(const bf16x8*)kp, a1 = *(const bf16x8*)(kp + 64);
;             f32x4 z = {0.f, 0.f, 0.f, 0.f}; z = mfma32(a0, q0, z); st[kt] = mfma32(a1, q1, z); }
;         { const unsigned char* kp = lds + AT_KM + lc * 144 + 16 * g; const bf16x8 a0 = *(const bf16x8*)kp, a1 = *(const bf16x8*)(kp + 64);
;             f32x4 z = {0.f, 0.f, 0.f, 0.f}; z = mfma32(a0, q0, z); st[9] = mfma32(a1, q1, z); }
;         float mx = sink;
; #pragma unroll
;         for (int kt = 0; kt < 9; ++kt)
; #pragma unroll
;             for (int r = 0; r < 4; ++r) { const int dist = 128 + lc - 16 * kt - 4 * g - r; const int j = 16 * (qs + kt) + 4 * g + r;
;                 const bool valid = (dist >= 0) && (dist < 128) && (n >= 1) && (n >= 2 || j >= 128);
;                 const float lg = valid ? (st[kt][r] * 0.125f + hb[w * 128 + (dist & 127)]) : NEGV; st[kt][r] = lg; mx = fmaxf(mx, lg); }
; #pragma unroll
;         for (int r = 0; r < 4; ++r) { const int dist = tq - (4 * g + r); const bool valid = dist >= 0; const int bk = (dist >= 0 && dist < 128) ? bkt[dist & 127] : 31;
;             const float lg = valid ? (st[9][r] * 0.125f + rb[bk * 16 + head]) : NEGV; st[9][r] = lg; mx = fmaxf(mx, lg); }
.LBB0_323:
	v_add_u32_e32 v22, 0, v118
	ds_read_b128 v[150:153], v22
	ds_read_b128 v[154:157], v22 offset:64
	ds_read_b128 v[158:161], v22 offset:2304
	ds_read_b128 v[162:165], v22 offset:2368
	ds_read_b128 v[166:169], v22 offset:4608
	ds_read_b128 v[170:173], v22 offset:4672
	ds_read_b128 v[174:177], v22 offset:6912
	ds_read_b128 v[178:181], v22 offset:6976
	ds_read_b128 v[182:185], v22 offset:9216
	ds_read_b128 v[186:189], v22 offset:9280
	ds_read_b128 v[190:193], v22 offset:11520
	ds_read_b128 v[196:199], v22 offset:11584
	ds_read_b128 v[200:203], v22 offset:13824
	s_nop 0
	ds_read_b128 v[204:207], v22 offset:13888
	s_waitcnt lgkmcnt(13)
	v_mfma_f32_16x16x32_bf16 v[42:45], v[150:153], v[38:41], 0
	s_waitcnt lgkmcnt(12)
	v_mfma_f32_16x16x32_bf16 v[78:81], v[154:157], v[70:73], v[42:45]
	s_nop 5
	s_nop 0
	ds_read_b128 v[208:211], v22 offset:16128
	s_nop 0
	ds_read_b128 v[214:217], v22 offset:16192
	s_waitcnt lgkmcnt(13)
	v_mfma_f32_16x16x32_bf16 v[42:45], v[158:161], v[38:41], 0
	s_waitcnt lgkmcnt(12)
	v_mfma_f32_16x16x32_bf16 v[74:77], v[162:165], v[70:73], v[42:45]
	s_nop 5
	s_nop 0
	ds_read_b128 v[218:221], v22 offset:18432
	s_nop 0
	ds_read_b128 v[222:225], v22 offset:18496
	s_waitcnt lgkmcnt(13)
	v_mfma_f32_16x16x32_bf16 v[42:45], v[166:169], v[38:41], 0
	s_waitcnt lgkmcnt(12)
	v_mfma_f32_16x16x32_bf16 v[66:69], v[170:173], v[70:73], v[42:45]
	s_nop 5
	s_nop 0
	s_nop 0
	s_waitcnt lgkmcnt(11)
	v_mfma_f32_16x16x32_bf16 v[42:45], v[174:177], v[38:41], 0
	s_waitcnt lgkmcnt(10)
	v_mfma_f32_16x16x32_bf16 v[62:65], v[178:181], v[70:73], v[42:45]
	s_nop 5
	s_nop 0
	s_nop 0
	s_waitcnt lgkmcnt(9)
	v_mfma_f32_16x16x32_bf16 v[42:45], v[182:185], v[38:41], 0
	s_waitcnt lgkmcnt(8)
	v_mfma_f32_16x16x32_bf16 v[58:61], v[186:189], v[70:73], v[42:45]
	s_nop 5
	s_nop 0
	s_nop 0
	s_waitcnt lgkmcnt(7)
	v_mfma_f32_16x16x32_bf16 v[42:45], v[190:193], v[38:41], 0
	s_waitcnt lgkmcnt(6)
	v_mfma_f32_16x16x32_bf16 v[54:57], v[196:199], v[70:73], v[42:45]
	s_nop 5
	s_nop 0
	s_nop 0
	s_waitcnt lgkmcnt(5)
	v_mfma_f32_16x16x32_bf16 v[42:45], v[200:203], v[38:41], 0
	s_waitcnt lgkmcnt(4)
	v_mfma_f32_16x16x32_bf16 v[50:53], v[204:207], v[70:73], v[42:45]
	s_nop 5
	s_nop 0
	s_nop 0
	s_waitcnt lgkmcnt(3)
	v_mfma_f32_16x16x32_bf16 v[42:45], v[208:211], v[38:41], 0
	s_waitcnt lgkmcnt(2)
	v_mfma_f32_16x16x32_bf16 v[46:49], v[214:217], v[70:73], v[42:45]
	s_nop 5
	s_nop 0
	s_nop 0
	s_waitcnt lgkmcnt(1)
	v_mfma_f32_16x16x32_bf16 v[42:45], v[218:221], v[38:41], 0
	v_mfma_f32_16x16x32_bf16 v[38:41], v[10:13], v[38:41], 0
	s_waitcnt lgkmcnt(0)
	v_mfma_f32_16x16x32_bf16 v[42:45], v[222:225], v[70:73], v[42:45]
	v_mfma_f32_16x16x32_bf16 v[38:41], v[18:21], v[70:73], v[38:41]
	v_add_u32_e32 v164, 0x26e34, v122
	ds_read_b32 v128, v111 offset:512
	ds_read_b32 v129, v112 offset:512
	ds_read_b32 v130, v113 offset:512
	ds_read_b32 v131, v114 offset:512
	ds_read_b32 v132, v111 offset:436
	ds_read_b32 v133, v111 offset:384
	ds_read_b32 v134, v111 offset:380
	ds_read_b32 v135, v111 offset:376
	ds_read_b32 v136, v111 offset:372
	ds_read_b32 v137, v111 offset:320
	ds_read_b32 v138, v111 offset:316
	ds_read_b32 v139, v111 offset:312
	ds_read_b32 v140, v111 offset:308
	ds_read_b32 v141, v111 offset:256
	ds_read_b32 v142, v111 offset:252
	ds_read_b32 v143, v111 offset:248
	ds_read_b32 v144, v111 offset:244
	ds_read_b32 v145, v111 offset:192
	ds_read_b32 v146, v111 offset:188
	ds_read_b32 v147, v111 offset:184
	ds_read_b32 v148, v111 offset:180
	ds_read_b32 v149, v111 offset:128
	ds_read_b32 v150, v111 offset:124
	ds_read_b32 v151, v111 offset:120
	ds_read_b32 v152, v111 offset:116
	ds_read_b32 v153, v111 offset:64
	ds_read_b32 v154, v111 offset:60
	ds_read_b32 v155, v111 offset:56
	ds_read_b32 v156, v111 offset:52
	ds_read_b32 v157, v111
	ds_read_b32 v158, v115 offset:512
	ds_read_b32 v159, v116 offset:512
	ds_read_b32 v160, v117 offset:512
	ds_read_b32 v161, v111 offset:448
	ds_read_b32 v162, v111 offset:444
	ds_read_b32 v163, v111 offset:440
	ds_read_b32 v165, v164
	ds_read_b32 v166, v164 offset:4
	ds_read_b32 v167, v164 offset:8
	ds_read_b32 v168, v164 offset:12
	s_waitcnt lgkmcnt(0)
	v_mov_b32_e32 v70, 0xf149f2ca
	v_mov_b32_e32 v73, 0xf149f2ca
	s_and_saveexec_b64 s[12:13], s[8:9]
	s_cbranch_execz .LBB0_325
	v_fmamk_f32 v73, v78, 0x3e000000, v128

; __device__ __forceinline__ void attn_unit(const Ptrs& P, int l, int b, int gk, int n, unsigned char* lds, int tid, bool dost) {
;     ...
;         for (int r = 0; r < 4; ++r) { const int dist = tq - (4 * g + r); const bool valid = dist >= 0; const int bk = (dist >= 0 && dist < 128) ? bkt[dist & 127] : 31;
;             const float lg = valid ? (st[9][r] * 0.125f + rb[bk * 16 + head]) : NEGV; st[9][r] = lg; mx = fmaxf(mx, lg); }
.LBB0_410:
	s_or_b64 exec, exec, s[12:13]
	v_add_u32_e32 v46, s15, v123
	v_add_u32_e32 v44, 0xffffff90, v46
	v_cmp_gt_u32_e32 vcc, s25, v44
	v_mov_b32_e32 v75, 0x1f0
	v_add_u32_e32 v45, 0, v122
	s_and_saveexec_b64 s[12:13], vcc
	s_cbranch_execz .LBB0_412
	v_mov_b32_e32 v75, v168
	v_lshlrev_b32_e32 v75, 4, v75

; __device__ __forceinline__ void attn_unit(const Ptrs& P, int l, int b, int gk, int n, unsigned char* lds, int tid, bool dost) {
;     ...
;         for (int r = 0; r < 4; ++r) { const int dist = tq - (4 * g + r); const bool valid = dist >= 0; const int bk = (dist >= 0 && dist < 128) ? bkt[dist & 127] : 31;
;             const float lg = valid ? (st[9][r] * 0.125f + rb[bk * 16 + head]) : NEGV; st[9][r] = lg; mx = fmaxf(mx, lg); }
.LBB0_414:
	s_or_b64 exec, exec, s[12:13]
	v_add_u32_e32 v38, 0xffffff8f, v46
	v_cmp_gt_u32_e32 vcc, s25, v38
	v_mov_b32_e32 v75, 0x1f0
	s_and_saveexec_b64 s[12:13], vcc
	s_cbranch_execz .LBB0_416
	v_mov_b32_e32 v75, v167
	v_lshlrev_b32_e32 v75, 4, v75

; __device__ __forceinline__ void attn_unit(const Ptrs& P, int l, int b, int gk, int n, unsigned char* lds, int tid, bool dost) {
;     ...
;         for (int r = 0; r < 4; ++r) { const int dist = tq - (4 * g + r); const bool valid = dist >= 0; const int bk = (dist >= 0 && dist < 128) ? bkt[dist & 127] : 31;
;             const float lg = valid ? (st[9][r] * 0.125f + rb[bk * 16 + head]) : NEGV; st[9][r] = lg; mx = fmaxf(mx, lg); }
.LBB0_418:
	s_or_b64 exec, exec, s[12:13]
	v_add_u32_e32 v39, 0xffffff8e, v46
	v_cmp_gt_u32_e32 vcc, s25, v39
	v_mov_b32_e32 v75, 0x1f0
	s_and_saveexec_b64 s[12:13], vcc
	s_cbranch_execz .LBB0_420
	v_mov_b32_e32 v75, v166
	v_lshlrev_b32_e32 v75, 4, v75

; __device__ __forceinline__ void attn_unit(const Ptrs& P, int l, int b, int gk, int n, unsigned char* lds, int tid, bool dost) {
;     ...
;         for (int r = 0; r < 4; ++r) { const int dist = tq - (4 * g + r); const bool valid = dist >= 0; const int bk = (dist >= 0 && dist < 128) ? bkt[dist & 127] : 31;
;             const float lg = valid ? (st[9][r] * 0.125f + rb[bk * 16 + head]) : NEGV; st[9][r] = lg; mx = fmaxf(mx, lg); }
.LBB0_422:
	s_or_b64 exec, exec, s[12:13]
	v_add_u32_e32 v40, 0xffffff8d, v46
	v_cmp_gt_u32_e32 vcc, s25, v40
	v_mov_b32_e32 v46, 0x1f0
	s_and_saveexec_b64 s[12:13], vcc
	s_cbranch_execz .LBB0_424
	v_mov_b32_e32 v45, v165
	v_lshlrev_b32_e32 v46, 4, v45
